# PEER gather: the eight waves of a CU start the gather about half a microsecond apart so their per-token sort and epilogue gaps do not coincide
# baseline (speedup 1.0000x reference)
; DEV int ltid() { int t = threadIdx.x; asm volatile("" : "+v"(t)); return t; }
; DEV float bflo(unsigned u) { return __uint_as_float(u << 16); }
; DEV float bfhi(unsigned u) { return __uint_as_float(u & 0xffff0000u); }
; DEV void peer_gather_token(const Params& p, int tok) {
;   const int lane = ltid() & 63, b = tok >> 11;
;   float hx[32], acc[32];
;   {
;     const u16* hr = p.h + (size_t)tok * 2048 + lane * 32;
; #pragma unroll
;     for (int q = 0; q < 4; ++q) {
;       u32x4 v = *(const u32x4*)(hr + q * 8);
; #pragma unroll
;       for (int e = 0; e < 4; ++e) { hx[q * 8 + 2 * e] = bflo(v[e]); hx[q * 8 + 2 * e + 1] = bfhi(v[e]); }
;     }
;   }
; #pragma unroll
;   for (int e = 0; e < 32; ++e) acc[e] = 0.f;
;   const int e0 = p.eidx[(size_t)tok * 128 + lane], e1 = p.eidx[(size_t)tok * 128 + 64 + lane];
;   const int g0 = __builtin_bit_cast(int, p.gw[(size_t)tok * 128 + lane]), g1 = __builtin_bit_cast(int, p.gw[(size_t)tok * 128 + 64 + lane]);
;   u32x2 dn[4][3], up[4][3];
;   auto issue = [&](int k, int slot) {
;     const int e = (k < 64) ? __builtin_amdgcn_readlane(e0, k) : __builtin_amdgcn_readlane(e1, k - 64);
;     const unsigned char* dr = p.down8 + (size_t)e * ROW6 + lane * 24;
;     const unsigned char* ur = p.up8 + (size_t)e * ROW6 + lane * 24;
; #pragma unroll
;     for (int i = 0; i < 3; ++i) { dn[slot][i] = *(const u32x2*)(dr + i * 8); up[slot][i] = *(const u32x2*)(ur + i * 8); }
;   };
;   issue(0, 0); issue(1, 1); issue(2, 2);
.LBB0_1567:
	s_or_b64 exec, exec, s[0:1]
	s_waitcnt lgkmcnt(0)
	s_barrier
	s_mov_b64 exec, -1
	v_lshrrev_b32_e32 v2, 6, v0
	v_and_b32_e32 v3, 63, v0
	s_nop 0
	v_readfirstlane_b32 s38, v2
	s_add_i32 s20, s84, s38
	s_mov_b32 s90, s38
	s_lshl_b32 s21, s92, 2
	s_cmpk_lt_u32 s20, 0x4000
	s_cbranch_scc0 .Lp12_end
	v_lshlrev_b32_e32 v1, 4, v3
	v_lshlrev_b32_e32 v242, 2, v3
	v_lshlrev_b32_e32 v243, 3, v3
	v_lshlrev_b32_e32 v244, 4, v3
	v_add_u32_e32 v245, 0x1000, v244
	v_lshrrev_b32_e32 v2, 3, v3
	v_and_b32_e32 v246, 7, v3
	v_lshlrev_b32_e32 v2, 20, v2
	v_lshl_or_b32 v246, v246, 3, v2
	v_add_u32_e32 v247, 0x800000, v246
	v_add_u32_e32 v248, 0x1000000, v246
	v_add_u32_e32 v249, 0x1800000, v246
	v_add_u32_e32 v250, 0x2000000, v246
	v_add_u32_e32 v251, 0x2800000, v246
	v_add_u32_e32 v252, 0x3000000, v246
	v_add_u32_e32 v253, 0x3800000, v246
	v_mov_b32_e32 v212, 0x3c800000
	v_mov_b32_e32 v213, 0x3ba10414
	v_mov_b32_e32 v214, 0xb9c68948
	v_mov_b32_e32 v215, 0x7f800000
	v_mov_b32_e32 v207, 0
	s_mov_b32 s9, 0x378e98ab
	s_mov_b32 s10, 0x3b7cd369
	s_mov_b32 s11, 0xbcc618b2
	s_mov_b32 s12, 0x3dda74e4
	s_mov_b32 s13, 0x3f228afd
	s_mov_b32 s14, 0x3e03c728
	s_mov_b32 s15, 0xbfb8aa3b
	s_mov_b32 s16, 0x42ce8ed0
	s_mov_b32 s17, 0xc2b17218
	s_brev_b32 s18, -2
	s_mov_b32 s43, 1
	s_mov_b32 s19, 0
	v_lshrrev_b32_e32 v2, 6, v0
	s_nop 0
	v_readfirstlane_b32 s38, v2
	s_lshr_b32 s39, s84, 10
	s_lshl_b32 s39, s39, 2
	s_add_u32 s38, s38, s39
.Lp12_stag:
	s_cmp_eq_u32 s38, 0
	s_cbranch_scc1 .Lp12_stag_done
	s_sleep 16
	s_sub_u32 s38, s38, 1
	s_branch .Lp12_stag
.Lp12_stag_done:
	s_lshl_b32 s38, s20, 9
	s_add_u32 s58, s66, s38
	s_addc_u32 s59, s67, 0
	global_load_dword v216, v242, s[58:59]
	global_load_dword v217, v242, s[58:59] offset:256
	s_add_u32 s58, s68, s38
	s_addc_u32 s59, s69, 0
	global_load_dword v218, v242, s[58:59]
	global_load_dword v219, v242, s[58:59] offset:256
	s_lshl_b32 s38, s20, 6
	s_add_u32 s58, s80, s38
	s_addc_u32 s59, s81, 0
	global_load_dwordx2 v[220:221], v246, s[58:59]
	global_load_dwordx2 v[222:223], v247, s[58:59]
	global_load_dwordx2 v[224:225], v248, s[58:59]
	global_load_dwordx2 v[226:227], v249, s[58:59]
	global_load_dwordx2 v[228:229], v250, s[58:59]
	global_load_dwordx2 v[230:231], v251, s[58:59]
	global_load_dwordx2 v[232:233], v252, s[58:59]
	global_load_dwordx2 v[234:235], v253, s[58:59]
	s_waitcnt vmcnt(0) lgkmcnt(0)
	s_mov_b32 s36, 0
	s_mov_b32 s37, 0
	v_and_b32_e32 v236, 63, v0
	v_lshrrev_b32_e32 v241, 6, v0
	v_lshl_or_b32 v237, v216, 7, v236
	v_or_b32_e32 v238, 64, v236
	v_lshl_or_b32 v238, v217, 7, v238
	v_mov_b32_e32 v239, 0
	v_mov_b32_e32 v240, 0
	v_lshlrev_b32_e32 v241, 10, v241
	v_lshl_add_u32 v241, v236, 2, v241
	v_readlane_b32 s46, v237, 0
	v_readlane_b32 s47, v238, 0
	s_nop 1
	v_cmp_lt_u32_e64 s[48:49], s46, v237
	v_cmp_lt_u32_e64 s[50:51], s46, v238
	v_cmp_lt_u32_e64 s[52:53], s47, v237
	v_cmp_lt_u32_e64 s[54:55], s47, v238
	v_readlane_b32 s46, v237, 1
	v_readlane_b32 s47, v238, 1
	v_addc_co_u32_e64 v239, s[56:57], 0, v239, s[48:49]
	v_addc_co_u32_e64 v240, s[56:57], 0, v240, s[50:51]
	v_addc_co_u32_e64 v239, s[56:57], 0, v239, s[52:53]
	v_addc_co_u32_e64 v240, s[56:57], 0, v240, s[54:55]
	v_cmp_lt_u32_e64 s[48:49], s46, v237
	v_cmp_lt_u32_e64 s[50:51], s46, v238
	v_cmp_lt_u32_e64 s[52:53], s47, v237
	v_cmp_lt_u32_e64 s[54:55], s47, v238
	v_readlane_b32 s46, v237, 2
	v_readlane_b32 s47, v238, 2
	v_addc_co_u32_e64 v239, s[56:57], 0, v239, s[48:49]
	v_addc_co_u32_e64 v240, s[56:57], 0, v240, s[50:51]
	v_addc_co_u32_e64 v239, s[56:57], 0, v239, s[52:53]
	v_addc_co_u32_e64 v240, s[56:57], 0, v240, s[54:55]
	v_cmp_lt_u32_e64 s[48:49], s46, v237
	v_cmp_lt_u32_e64 s[50:51], s46, v238
	v_cmp_lt_u32_e64 s[52:53], s47, v237
	v_cmp_lt_u32_e64 s[54:55], s47, v238
	v_readlane_b32 s46, v237, 3
	v_readlane_b32 s47, v238, 3
	v_addc_co_u32_e64 v239, s[56:57], 0, v239, s[48:49]
	v_addc_co_u32_e64 v240, s[56:57], 0, v240, s[50:51]
	v_addc_co_u32_e64 v239, s[56:57], 0, v239, s[52:53]
	v_addc_co_u32_e64 v240, s[56:57], 0, v240, s[54:55]
	v_cmp_lt_u32_e64 s[48:49], s46, v237
	v_cmp_lt_u32_e64 s[50:51], s46, v238
	v_cmp_lt_u32_e64 s[52:53], s47, v237
	v_cmp_lt_u32_e64 s[54:55], s47, v238
	v_readlane_b32 s46, v237, 4
	v_readlane_b32 s47, v238, 4
	v_addc_co_u32_e64 v239, s[56:57], 0, v239, s[48:49]
	v_addc_co_u32_e64 v240, s[56:57], 0, v240, s[50:51]
	v_addc_co_u32_e64 v239, s[56:57], 0, v239, s[52:53]
	v_addc_co_u32_e64 v240, s[56:57], 0, v240, s[54:55]
	v_cmp_lt_u32_e64 s[48:49], s46, v237
	v_cmp_lt_u32_e64 s[50:51], s46, v238
	v_cmp_lt_u32_e64 s[52:53], s47, v237
	v_cmp_lt_u32_e64 s[54:55], s47, v238
	v_readlane_b32 s46, v237, 5
	v_readlane_b32 s47, v238, 5
	v_addc_co_u32_e64 v239, s[56:57], 0, v239, s[48:49]
	v_addc_co_u32_e64 v240, s[56:57], 0, v240, s[50:51]
	v_addc_co_u32_e64 v239, s[56:57], 0, v239, s[52:53]
	v_addc_co_u32_e64 v240, s[56:57], 0, v240, s[54:55]
	v_cmp_lt_u32_e64 s[48:49], s46, v237
	v_cmp_lt_u32_e64 s[50:51], s46, v238
	v_cmp_lt_u32_e64 s[52:53], s47, v237
	v_cmp_lt_u32_e64 s[54:55], s47, v238
	v_readlane_b32 s46, v237, 6
	v_readlane_b32 s47, v238, 6
	v_addc_co_u32_e64 v239, s[56:57], 0, v239, s[48:49]
	v_addc_co_u32_e64 v240, s[56:57], 0, v240, s[50:51]
	v_addc_co_u32_e64 v239, s[56:57], 0, v239, s[52:53]
	v_addc_co_u32_e64 v240, s[56:57], 0, v240, s[54:55]
	v_cmp_lt_u32_e64 s[48:49], s46, v237
	v_cmp_lt_u32_e64 s[50:51], s46, v238
	v_cmp_lt_u32_e64 s[52:53], s47, v237
	v_cmp_lt_u32_e64 s[54:55], s47, v238
	v_readlane_b32 s46, v237, 7
	v_readlane_b32 s47, v238, 7
	v_addc_co_u32_e64 v239, s[56:57], 0, v239, s[48:49]
	v_addc_co_u32_e64 v240, s[56:57], 0, v240, s[50:51]
	v_addc_co_u32_e64 v239, s[56:57], 0, v239, s[52:53]
; DEV void peer_gather_token(const Params& p, int tok) {
;     ...
;   const int e0 = p.eidx[(size_t)tok * 128 + lane], e1 = p.eidx[(size_t)tok * 128 + 64 + lane];
;   const int g0 = __builtin_bit_cast(int, p.gw[(size_t)tok * 128 + lane]), g1 = __builtin_bit_cast(int, p.gw[(size_t)tok * 128 + 64 + lane]);
;   u32x2 dn[4][3], up[4][3];
;   auto issue = [&](int k, int slot) {
;     const int e = (k < 64) ? __builtin_amdgcn_readlane(e0, k) : __builtin_amdgcn_readlane(e1, k - 64);
;     const unsigned char* dr = p.down8 + (size_t)e * ROW6 + lane * 24;
;     const unsigned char* ur = p.up8 + (size_t)e * ROW6 + lane * 24;
; #pragma unroll
;     for (int i = 0; i < 3; ++i) { dn[slot][i] = *(const u32x2*)(dr + i * 8); up[slot][i] = *(const u32x2*)(ur + i * 8); }
;   };
	v_addc_co_u32_e64 v240, s[56:57], 0, v240, s[54:55]
	v_cmp_lt_u32_e64 s[48:49], s46, v237
	v_cmp_lt_u32_e64 s[50:51], s46, v238
	v_cmp_lt_u32_e64 s[52:53], s47, v237
	v_cmp_lt_u32_e64 s[54:55], s47, v238
	v_readlane_b32 s46, v237, 8
	v_readlane_b32 s47, v238, 8
	v_addc_co_u32_e64 v239, s[56:57], 0, v239, s[48:49]
	v_addc_co_u32_e64 v240, s[56:57], 0, v240, s[50:51]
	v_addc_co_u32_e64 v239, s[56:57], 0, v239, s[52:53]
	v_addc_co_u32_e64 v240, s[56:57], 0, v240, s[54:55]
	v_cmp_lt_u32_e64 s[48:49], s46, v237
	v_cmp_lt_u32_e64 s[50:51], s46, v238
	v_cmp_lt_u32_e64 s[52:53], s47, v237
	v_cmp_lt_u32_e64 s[54:55], s47, v238
	v_readlane_b32 s46, v237, 9
	v_readlane_b32 s47, v238, 9
	v_addc_co_u32_e64 v239, s[56:57], 0, v239, s[48:49]
	v_addc_co_u32_e64 v240, s[56:57], 0, v240, s[50:51]
	v_addc_co_u32_e64 v239, s[56:57], 0, v239, s[52:53]
	v_addc_co_u32_e64 v240, s[56:57], 0, v240, s[54:55]
	v_cmp_lt_u32_e64 s[48:49], s46, v237
	v_cmp_lt_u32_e64 s[50:51], s46, v238
	v_cmp_lt_u32_e64 s[52:53], s47, v237
	v_cmp_lt_u32_e64 s[54:55], s47, v238
	v_readlane_b32 s46, v237, 10
	v_readlane_b32 s47, v238, 10
	v_addc_co_u32_e64 v239, s[56:57], 0, v239, s[48:49]
	v_addc_co_u32_e64 v240, s[56:57], 0, v240, s[50:51]
	v_addc_co_u32_e64 v239, s[56:57], 0, v239, s[52:53]
	v_addc_co_u32_e64 v240, s[56:57], 0, v240, s[54:55]
	v_cmp_lt_u32_e64 s[48:49], s46, v237
	v_cmp_lt_u32_e64 s[50:51], s46, v238
	v_cmp_lt_u32_e64 s[52:53], s47, v237
	v_cmp_lt_u32_e64 s[54:55], s47, v238
	v_readlane_b32 s46, v237, 11
	v_readlane_b32 s47, v238, 11
	v_addc_co_u32_e64 v239, s[56:57], 0, v239, s[48:49]
	v_addc_co_u32_e64 v240, s[56:57], 0, v240, s[50:51]
	v_addc_co_u32_e64 v239, s[56:57], 0, v239, s[52:53]
	v_addc_co_u32_e64 v240, s[56:57], 0, v240, s[54:55]
	v_cmp_lt_u32_e64 s[48:49], s46, v237
	v_cmp_lt_u32_e64 s[50:51], s46, v238
	v_cmp_lt_u32_e64 s[52:53], s47, v237
	v_cmp_lt_u32_e64 s[54:55], s47, v238
	v_readlane_b32 s46, v237, 12
	v_readlane_b32 s47, v238, 12
	v_addc_co_u32_e64 v239, s[56:57], 0, v239, s[48:49]
	v_addc_co_u32_e64 v240, s[56:57], 0, v240, s[50:51]
	v_addc_co_u32_e64 v239, s[56:57], 0, v239, s[52:53]
	v_addc_co_u32_e64 v240, s[56:57], 0, v240, s[54:55]
	v_cmp_lt_u32_e64 s[48:49], s46, v237
	v_cmp_lt_u32_e64 s[50:51], s46, v238
	v_cmp_lt_u32_e64 s[52:53], s47, v237
	v_cmp_lt_u32_e64 s[54:55], s47, v238
	v_readlane_b32 s46, v237, 13
	v_readlane_b32 s47, v238, 13
	v_addc_co_u32_e64 v239, s[56:57], 0, v239, s[48:49]
	v_addc_co_u32_e64 v240, s[56:57], 0, v240, s[50:51]
	v_addc_co_u32_e64 v239, s[56:57], 0, v239, s[52:53]
	v_addc_co_u32_e64 v240, s[56:57], 0, v240, s[54:55]
	v_cmp_lt_u32_e64 s[48:49], s46, v237
	v_cmp_lt_u32_e64 s[50:51], s46, v238
	v_cmp_lt_u32_e64 s[52:53], s47, v237
	v_cmp_lt_u32_e64 s[54:55], s47, v238
	v_readlane_b32 s46, v237, 14
	v_readlane_b32 s47, v238, 14
	v_addc_co_u32_e64 v239, s[56:57], 0, v239, s[48:49]
	v_addc_co_u32_e64 v240, s[56:57], 0, v240, s[50:51]
	v_addc_co_u32_e64 v239, s[56:57], 0, v239, s[52:53]
	v_addc_co_u32_e64 v240, s[56:57], 0, v240, s[54:55]
	v_cmp_lt_u32_e64 s[48:49], s46, v237
	v_cmp_lt_u32_e64 s[50:51], s46, v238
	v_cmp_lt_u32_e64 s[52:53], s47, v237
	v_cmp_lt_u32_e64 s[54:55], s47, v238
	v_readlane_b32 s46, v237, 15
	v_readlane_b32 s47, v238, 15
	v_addc_co_u32_e64 v239, s[56:57], 0, v239, s[48:49]
	v_addc_co_u32_e64 v240, s[56:57], 0, v240, s[50:51]
	v_addc_co_u32_e64 v239, s[56:57], 0, v239, s[52:53]
	v_addc_co_u32_e64 v240, s[56:57], 0, v240, s[54:55]
	v_cmp_lt_u32_e64 s[48:49], s46, v237
	v_cmp_lt_u32_e64 s[50:51], s46, v238
	v_cmp_lt_u32_e64 s[52:53], s47, v237
	v_cmp_lt_u32_e64 s[54:55], s47, v238
	v_readlane_b32 s46, v237, 16
	v_readlane_b32 s47, v238, 16
	v_addc_co_u32_e64 v239, s[56:57], 0, v239, s[48:49]
	v_addc_co_u32_e64 v240, s[56:57], 0, v240, s[50:51]
	v_addc_co_u32_e64 v239, s[56:57], 0, v239, s[52:53]
	v_addc_co_u32_e64 v240, s[56:57], 0, v240, s[54:55]
	v_cmp_lt_u32_e64 s[48:49], s46, v237
	v_cmp_lt_u32_e64 s[50:51], s46, v238
	v_cmp_lt_u32_e64 s[52:53], s47, v237
	v_cmp_lt_u32_e64 s[54:55], s47, v238
	v_readlane_b32 s46, v237, 17
	v_readlane_b32 s47, v238, 17
	v_addc_co_u32_e64 v239, s[56:57], 0, v239, s[48:49]
	v_addc_co_u32_e64 v240, s[56:57], 0, v240, s[50:51]
	v_addc_co_u32_e64 v239, s[56:57], 0, v239, s[52:53]
	v_addc_co_u32_e64 v240, s[56:57], 0, v240, s[54:55]
	v_cmp_lt_u32_e64 s[48:49], s46, v237
	v_cmp_lt_u32_e64 s[50:51], s46, v238
	v_cmp_lt_u32_e64 s[52:53], s47, v237
	v_cmp_lt_u32_e64 s[54:55], s47, v238
	v_readlane_b32 s46, v237, 18
	v_readlane_b32 s47, v238, 18
	v_addc_co_u32_e64 v239, s[56:57], 0, v239, s[48:49]
	v_addc_co_u32_e64 v240, s[56:57], 0, v240, s[50:51]
	v_addc_co_u32_e64 v239, s[56:57], 0, v239, s[52:53]
	v_addc_co_u32_e64 v240, s[56:57], 0, v240, s[54:55]
	v_cmp_lt_u32_e64 s[48:49], s46, v237
	v_cmp_lt_u32_e64 s[50:51], s46, v238
	v_cmp_lt_u32_e64 s[52:53], s47, v237
	v_cmp_lt_u32_e64 s[54:55], s47, v238
	v_readlane_b32 s46, v237, 19
	v_readlane_b32 s47, v238, 19
	v_addc_co_u32_e64 v239, s[56:57], 0, v239, s[48:49]
	v_addc_co_u32_e64 v240, s[56:57], 0, v240, s[50:51]
	v_addc_co_u32_e64 v239, s[56:57], 0, v239, s[52:53]
	v_addc_co_u32_e64 v240, s[56:57], 0, v240, s[54:55]
	v_cmp_lt_u32_e64 s[48:49], s46, v237
	v_cmp_lt_u32_e64 s[50:51], s46, v238
	v_cmp_lt_u32_e64 s[52:53], s47, v237
	v_cmp_lt_u32_e64 s[54:55], s47, v238
	v_readlane_b32 s46, v237, 20
	v_readlane_b32 s47, v238, 20
	v_addc_co_u32_e64 v239, s[56:57], 0, v239, s[48:49]
	v_addc_co_u32_e64 v240, s[56:57], 0, v240, s[50:51]
	v_addc_co_u32_e64 v239, s[56:57], 0, v239, s[52:53]
	v_addc_co_u32_e64 v240, s[56:57], 0, v240, s[54:55]
	v_cmp_lt_u32_e64 s[48:49], s46, v237
	v_cmp_lt_u32_e64 s[50:51], s46, v238
; DEV void peer_gather_token(const Params& p, int tok) {
;     ...
;   const int e0 = p.eidx[(size_t)tok * 128 + lane], e1 = p.eidx[(size_t)tok * 128 + 64 + lane];
;   const int g0 = __builtin_bit_cast(int, p.gw[(size_t)tok * 128 + lane]), g1 = __builtin_bit_cast(int, p.gw[(size_t)tok * 128 + 64 + lane]);
;   u32x2 dn[4][3], up[4][3];
;   auto issue = [&](int k, int slot) {
;     const int e = (k < 64) ? __builtin_amdgcn_readlane(e0, k) : __builtin_amdgcn_readlane(e1, k - 64);
;     const unsigned char* dr = p.down8 + (size_t)e * ROW6 + lane * 24;
;     const unsigned char* ur = p.up8 + (size_t)e * ROW6 + lane * 24;
; #pragma unroll
;     for (int i = 0; i < 3; ++i) { dn[slot][i] = *(const u32x2*)(dr + i * 8); up[slot][i] = *(const u32x2*)(ur + i * 8); }
;   };
	v_cmp_lt_u32_e64 s[52:53], s47, v237
	v_cmp_lt_u32_e64 s[54:55], s47, v238
	v_readlane_b32 s46, v237, 21
	v_readlane_b32 s47, v238, 21
	v_addc_co_u32_e64 v239, s[56:57], 0, v239, s[48:49]
	v_addc_co_u32_e64 v240, s[56:57], 0, v240, s[50:51]
	v_addc_co_u32_e64 v239, s[56:57], 0, v239, s[52:53]
	v_addc_co_u32_e64 v240, s[56:57], 0, v240, s[54:55]
	v_cmp_lt_u32_e64 s[48:49], s46, v237
	v_cmp_lt_u32_e64 s[50:51], s46, v238
	v_cmp_lt_u32_e64 s[52:53], s47, v237
	v_cmp_lt_u32_e64 s[54:55], s47, v238
	v_readlane_b32 s46, v237, 22
	v_readlane_b32 s47, v238, 22
	v_addc_co_u32_e64 v239, s[56:57], 0, v239, s[48:49]
	v_addc_co_u32_e64 v240, s[56:57], 0, v240, s[50:51]
	v_addc_co_u32_e64 v239, s[56:57], 0, v239, s[52:53]
	v_addc_co_u32_e64 v240, s[56:57], 0, v240, s[54:55]
	v_cmp_lt_u32_e64 s[48:49], s46, v237
	v_cmp_lt_u32_e64 s[50:51], s46, v238
	v_cmp_lt_u32_e64 s[52:53], s47, v237
	v_cmp_lt_u32_e64 s[54:55], s47, v238
	v_readlane_b32 s46, v237, 23
	v_readlane_b32 s47, v238, 23
	v_addc_co_u32_e64 v239, s[56:57], 0, v239, s[48:49]
	v_addc_co_u32_e64 v240, s[56:57], 0, v240, s[50:51]
	v_addc_co_u32_e64 v239, s[56:57], 0, v239, s[52:53]
	v_addc_co_u32_e64 v240, s[56:57], 0, v240, s[54:55]
	v_cmp_lt_u32_e64 s[48:49], s46, v237
	v_cmp_lt_u32_e64 s[50:51], s46, v238
	v_cmp_lt_u32_e64 s[52:53], s47, v237
	v_cmp_lt_u32_e64 s[54:55], s47, v238
	v_readlane_b32 s46, v237, 24
	v_readlane_b32 s47, v238, 24
	v_addc_co_u32_e64 v239, s[56:57], 0, v239, s[48:49]
	v_addc_co_u32_e64 v240, s[56:57], 0, v240, s[50:51]
	v_addc_co_u32_e64 v239, s[56:57], 0, v239, s[52:53]
	v_addc_co_u32_e64 v240, s[56:57], 0, v240, s[54:55]
	v_cmp_lt_u32_e64 s[48:49], s46, v237
	v_cmp_lt_u32_e64 s[50:51], s46, v238
	v_cmp_lt_u32_e64 s[52:53], s47, v237
	v_cmp_lt_u32_e64 s[54:55], s47, v238
	v_readlane_b32 s46, v237, 25
	v_readlane_b32 s47, v238, 25
	v_addc_co_u32_e64 v239, s[56:57], 0, v239, s[48:49]
	v_addc_co_u32_e64 v240, s[56:57], 0, v240, s[50:51]
	v_addc_co_u32_e64 v239, s[56:57], 0, v239, s[52:53]
	v_addc_co_u32_e64 v240, s[56:57], 0, v240, s[54:55]
	v_cmp_lt_u32_e64 s[48:49], s46, v237
	v_cmp_lt_u32_e64 s[50:51], s46, v238
	v_cmp_lt_u32_e64 s[52:53], s47, v237
	v_cmp_lt_u32_e64 s[54:55], s47, v238
	v_readlane_b32 s46, v237, 26
	v_readlane_b32 s47, v238, 26
	v_addc_co_u32_e64 v239, s[56:57], 0, v239, s[48:49]
	v_addc_co_u32_e64 v240, s[56:57], 0, v240, s[50:51]
	v_addc_co_u32_e64 v239, s[56:57], 0, v239, s[52:53]
	v_addc_co_u32_e64 v240, s[56:57], 0, v240, s[54:55]
	v_cmp_lt_u32_e64 s[48:49], s46, v237
	v_cmp_lt_u32_e64 s[50:51], s46, v238
	v_cmp_lt_u32_e64 s[52:53], s47, v237
	v_cmp_lt_u32_e64 s[54:55], s47, v238
	v_readlane_b32 s46, v237, 27
	v_readlane_b32 s47, v238, 27
	v_addc_co_u32_e64 v239, s[56:57], 0, v239, s[48:49]
	v_addc_co_u32_e64 v240, s[56:57], 0, v240, s[50:51]
	v_addc_co_u32_e64 v239, s[56:57], 0, v239, s[52:53]
	v_addc_co_u32_e64 v240, s[56:57], 0, v240, s[54:55]
	v_cmp_lt_u32_e64 s[48:49], s46, v237
	v_cmp_lt_u32_e64 s[50:51], s46, v238
	v_cmp_lt_u32_e64 s[52:53], s47, v237
	v_cmp_lt_u32_e64 s[54:55], s47, v238
	v_readlane_b32 s46, v237, 28
	v_readlane_b32 s47, v238, 28
	v_addc_co_u32_e64 v239, s[56:57], 0, v239, s[48:49]
	v_addc_co_u32_e64 v240, s[56:57], 0, v240, s[50:51]
	v_addc_co_u32_e64 v239, s[56:57], 0, v239, s[52:53]
	v_addc_co_u32_e64 v240, s[56:57], 0, v240, s[54:55]
	v_cmp_lt_u32_e64 s[48:49], s46, v237
	v_cmp_lt_u32_e64 s[50:51], s46, v238
	v_cmp_lt_u32_e64 s[52:53], s47, v237
	v_cmp_lt_u32_e64 s[54:55], s47, v238
	v_readlane_b32 s46, v237, 29
	v_readlane_b32 s47, v238, 29
	v_addc_co_u32_e64 v239, s[56:57], 0, v239, s[48:49]
	v_addc_co_u32_e64 v240, s[56:57], 0, v240, s[50:51]
	v_addc_co_u32_e64 v239, s[56:57], 0, v239, s[52:53]
	v_addc_co_u32_e64 v240, s[56:57], 0, v240, s[54:55]
	v_cmp_lt_u32_e64 s[48:49], s46, v237
	v_cmp_lt_u32_e64 s[50:51], s46, v238
	v_cmp_lt_u32_e64 s[52:53], s47, v237
	v_cmp_lt_u32_e64 s[54:55], s47, v238
	v_readlane_b32 s46, v237, 30
	v_readlane_b32 s47, v238, 30
	v_addc_co_u32_e64 v239, s[56:57], 0, v239, s[48:49]
	v_addc_co_u32_e64 v240, s[56:57], 0, v240, s[50:51]
	v_addc_co_u32_e64 v239, s[56:57], 0, v239, s[52:53]
	v_addc_co_u32_e64 v240, s[56:57], 0, v240, s[54:55]
	v_cmp_lt_u32_e64 s[48:49], s46, v237
	v_cmp_lt_u32_e64 s[50:51], s46, v238
	v_cmp_lt_u32_e64 s[52:53], s47, v237
	v_cmp_lt_u32_e64 s[54:55], s47, v238
	v_readlane_b32 s46, v237, 31
	v_readlane_b32 s47, v238, 31
	v_addc_co_u32_e64 v239, s[56:57], 0, v239, s[48:49]
	v_addc_co_u32_e64 v240, s[56:57], 0, v240, s[50:51]
	v_addc_co_u32_e64 v239, s[56:57], 0, v239, s[52:53]
	v_addc_co_u32_e64 v240, s[56:57], 0, v240, s[54:55]
	v_cmp_lt_u32_e64 s[48:49], s46, v237
	v_cmp_lt_u32_e64 s[50:51], s46, v238
	v_cmp_lt_u32_e64 s[52:53], s47, v237
	v_cmp_lt_u32_e64 s[54:55], s47, v238
	v_readlane_b32 s46, v237, 32
	v_readlane_b32 s47, v238, 32
	v_addc_co_u32_e64 v239, s[56:57], 0, v239, s[48:49]
	v_addc_co_u32_e64 v240, s[56:57], 0, v240, s[50:51]
	v_addc_co_u32_e64 v239, s[56:57], 0, v239, s[52:53]
	v_addc_co_u32_e64 v240, s[56:57], 0, v240, s[54:55]
	v_cmp_lt_u32_e64 s[48:49], s46, v237
	v_cmp_lt_u32_e64 s[50:51], s46, v238
	v_cmp_lt_u32_e64 s[52:53], s47, v237
	v_cmp_lt_u32_e64 s[54:55], s47, v238
	v_readlane_b32 s46, v237, 33
	v_readlane_b32 s47, v238, 33
	v_addc_co_u32_e64 v239, s[56:57], 0, v239, s[48:49]
	v_addc_co_u32_e64 v240, s[56:57], 0, v240, s[50:51]
	v_addc_co_u32_e64 v239, s[56:57], 0, v239, s[52:53]
	v_addc_co_u32_e64 v240, s[56:57], 0, v240, s[54:55]
	v_cmp_lt_u32_e64 s[48:49], s46, v237
	v_cmp_lt_u32_e64 s[50:51], s46, v238
	v_cmp_lt_u32_e64 s[52:53], s47, v237
	v_cmp_lt_u32_e64 s[54:55], s47, v238
	v_readlane_b32 s46, v237, 34
	v_readlane_b32 s47, v238, 34
; DEV void peer_gather_token(const Params& p, int tok) {
;     ...
;   const int e0 = p.eidx[(size_t)tok * 128 + lane], e1 = p.eidx[(size_t)tok * 128 + 64 + lane];
;   const int g0 = __builtin_bit_cast(int, p.gw[(size_t)tok * 128 + lane]), g1 = __builtin_bit_cast(int, p.gw[(size_t)tok * 128 + 64 + lane]);
;   u32x2 dn[4][3], up[4][3];
;   auto issue = [&](int k, int slot) {
;     const int e = (k < 64) ? __builtin_amdgcn_readlane(e0, k) : __builtin_amdgcn_readlane(e1, k - 64);
;     const unsigned char* dr = p.down8 + (size_t)e * ROW6 + lane * 24;
;     const unsigned char* ur = p.up8 + (size_t)e * ROW6 + lane * 24;
; #pragma unroll
;     for (int i = 0; i < 3; ++i) { dn[slot][i] = *(const u32x2*)(dr + i * 8); up[slot][i] = *(const u32x2*)(ur + i * 8); }
;   };
	v_addc_co_u32_e64 v239, s[56:57], 0, v239, s[48:49]
	v_addc_co_u32_e64 v240, s[56:57], 0, v240, s[50:51]
	v_addc_co_u32_e64 v239, s[56:57], 0, v239, s[52:53]
	v_addc_co_u32_e64 v240, s[56:57], 0, v240, s[54:55]
	v_cmp_lt_u32_e64 s[48:49], s46, v237
	v_cmp_lt_u32_e64 s[50:51], s46, v238
	v_cmp_lt_u32_e64 s[52:53], s47, v237
	v_cmp_lt_u32_e64 s[54:55], s47, v238
	v_readlane_b32 s46, v237, 35
	v_readlane_b32 s47, v238, 35
	v_addc_co_u32_e64 v239, s[56:57], 0, v239, s[48:49]
	v_addc_co_u32_e64 v240, s[56:57], 0, v240, s[50:51]
	v_addc_co_u32_e64 v239, s[56:57], 0, v239, s[52:53]
	v_addc_co_u32_e64 v240, s[56:57], 0, v240, s[54:55]
	v_cmp_lt_u32_e64 s[48:49], s46, v237
	v_cmp_lt_u32_e64 s[50:51], s46, v238
	v_cmp_lt_u32_e64 s[52:53], s47, v237
	v_cmp_lt_u32_e64 s[54:55], s47, v238
	v_readlane_b32 s46, v237, 36
	v_readlane_b32 s47, v238, 36
	v_addc_co_u32_e64 v239, s[56:57], 0, v239, s[48:49]
	v_addc_co_u32_e64 v240, s[56:57], 0, v240, s[50:51]
	v_addc_co_u32_e64 v239, s[56:57], 0, v239, s[52:53]
	v_addc_co_u32_e64 v240, s[56:57], 0, v240, s[54:55]
	v_cmp_lt_u32_e64 s[48:49], s46, v237
	v_cmp_lt_u32_e64 s[50:51], s46, v238
	v_cmp_lt_u32_e64 s[52:53], s47, v237
	v_cmp_lt_u32_e64 s[54:55], s47, v238
	v_readlane_b32 s46, v237, 37
	v_readlane_b32 s47, v238, 37
	v_addc_co_u32_e64 v239, s[56:57], 0, v239, s[48:49]
	v_addc_co_u32_e64 v240, s[56:57], 0, v240, s[50:51]
	v_addc_co_u32_e64 v239, s[56:57], 0, v239, s[52:53]
	v_addc_co_u32_e64 v240, s[56:57], 0, v240, s[54:55]
	v_cmp_lt_u32_e64 s[48:49], s46, v237
	v_cmp_lt_u32_e64 s[50:51], s46, v238
	v_cmp_lt_u32_e64 s[52:53], s47, v237
	v_cmp_lt_u32_e64 s[54:55], s47, v238
	v_readlane_b32 s46, v237, 38
	v_readlane_b32 s47, v238, 38
	v_addc_co_u32_e64 v239, s[56:57], 0, v239, s[48:49]
	v_addc_co_u32_e64 v240, s[56:57], 0, v240, s[50:51]
	v_addc_co_u32_e64 v239, s[56:57], 0, v239, s[52:53]
	v_addc_co_u32_e64 v240, s[56:57], 0, v240, s[54:55]
	v_cmp_lt_u32_e64 s[48:49], s46, v237
	v_cmp_lt_u32_e64 s[50:51], s46, v238
	v_cmp_lt_u32_e64 s[52:53], s47, v237
	v_cmp_lt_u32_e64 s[54:55], s47, v238
	v_readlane_b32 s46, v237, 39
	v_readlane_b32 s47, v238, 39
	v_addc_co_u32_e64 v239, s[56:57], 0, v239, s[48:49]
	v_addc_co_u32_e64 v240, s[56:57], 0, v240, s[50:51]
	v_addc_co_u32_e64 v239, s[56:57], 0, v239, s[52:53]
	v_addc_co_u32_e64 v240, s[56:57], 0, v240, s[54:55]
	v_cmp_lt_u32_e64 s[48:49], s46, v237
	v_cmp_lt_u32_e64 s[50:51], s46, v238
	v_cmp_lt_u32_e64 s[52:53], s47, v237
	v_cmp_lt_u32_e64 s[54:55], s47, v238
	v_readlane_b32 s46, v237, 40
	v_readlane_b32 s47, v238, 40
	v_addc_co_u32_e64 v239, s[56:57], 0, v239, s[48:49]
	v_addc_co_u32_e64 v240, s[56:57], 0, v240, s[50:51]
	v_addc_co_u32_e64 v239, s[56:57], 0, v239, s[52:53]
	v_addc_co_u32_e64 v240, s[56:57], 0, v240, s[54:55]
	v_cmp_lt_u32_e64 s[48:49], s46, v237
	v_cmp_lt_u32_e64 s[50:51], s46, v238
	v_cmp_lt_u32_e64 s[52:53], s47, v237
	v_cmp_lt_u32_e64 s[54:55], s47, v238
	v_readlane_b32 s46, v237, 41
	v_readlane_b32 s47, v238, 41
	v_addc_co_u32_e64 v239, s[56:57], 0, v239, s[48:49]
	v_addc_co_u32_e64 v240, s[56:57], 0, v240, s[50:51]
	v_addc_co_u32_e64 v239, s[56:57], 0, v239, s[52:53]
	v_addc_co_u32_e64 v240, s[56:57], 0, v240, s[54:55]
	v_cmp_lt_u32_e64 s[48:49], s46, v237
	v_cmp_lt_u32_e64 s[50:51], s46, v238
	v_cmp_lt_u32_e64 s[52:53], s47, v237
	v_cmp_lt_u32_e64 s[54:55], s47, v238
	v_readlane_b32 s46, v237, 42
	v_readlane_b32 s47, v238, 42
	v_addc_co_u32_e64 v239, s[56:57], 0, v239, s[48:49]
	v_addc_co_u32_e64 v240, s[56:57], 0, v240, s[50:51]
	v_addc_co_u32_e64 v239, s[56:57], 0, v239, s[52:53]
	v_addc_co_u32_e64 v240, s[56:57], 0, v240, s[54:55]
	v_cmp_lt_u32_e64 s[48:49], s46, v237
	v_cmp_lt_u32_e64 s[50:51], s46, v238
	v_cmp_lt_u32_e64 s[52:53], s47, v237
	v_cmp_lt_u32_e64 s[54:55], s47, v238
	v_readlane_b32 s46, v237, 43
	v_readlane_b32 s47, v238, 43
	v_addc_co_u32_e64 v239, s[56:57], 0, v239, s[48:49]
	v_addc_co_u32_e64 v240, s[56:57], 0, v240, s[50:51]
	v_addc_co_u32_e64 v239, s[56:57], 0, v239, s[52:53]
	v_addc_co_u32_e64 v240, s[56:57], 0, v240, s[54:55]
	v_cmp_lt_u32_e64 s[48:49], s46, v237
	v_cmp_lt_u32_e64 s[50:51], s46, v238
	v_cmp_lt_u32_e64 s[52:53], s47, v237
	v_cmp_lt_u32_e64 s[54:55], s47, v238
	v_readlane_b32 s46, v237, 44
	v_readlane_b32 s47, v238, 44
	v_addc_co_u32_e64 v239, s[56:57], 0, v239, s[48:49]
	v_addc_co_u32_e64 v240, s[56:57], 0, v240, s[50:51]
	v_addc_co_u32_e64 v239, s[56:57], 0, v239, s[52:53]
	v_addc_co_u32_e64 v240, s[56:57], 0, v240, s[54:55]
	v_cmp_lt_u32_e64 s[48:49], s46, v237
	v_cmp_lt_u32_e64 s[50:51], s46, v238
	v_cmp_lt_u32_e64 s[52:53], s47, v237
	v_cmp_lt_u32_e64 s[54:55], s47, v238
	v_readlane_b32 s46, v237, 45
	v_readlane_b32 s47, v238, 45
	v_addc_co_u32_e64 v239, s[56:57], 0, v239, s[48:49]
	v_addc_co_u32_e64 v240, s[56:57], 0, v240, s[50:51]
	v_addc_co_u32_e64 v239, s[56:57], 0, v239, s[52:53]
	v_addc_co_u32_e64 v240, s[56:57], 0, v240, s[54:55]
	v_cmp_lt_u32_e64 s[48:49], s46, v237
	v_cmp_lt_u32_e64 s[50:51], s46, v238
	v_cmp_lt_u32_e64 s[52:53], s47, v237
	v_cmp_lt_u32_e64 s[54:55], s47, v238
	v_readlane_b32 s46, v237, 46
	v_readlane_b32 s47, v238, 46
	v_addc_co_u32_e64 v239, s[56:57], 0, v239, s[48:49]
	v_addc_co_u32_e64 v240, s[56:57], 0, v240, s[50:51]
	v_addc_co_u32_e64 v239, s[56:57], 0, v239, s[52:53]
	v_addc_co_u32_e64 v240, s[56:57], 0, v240, s[54:55]
	v_cmp_lt_u32_e64 s[48:49], s46, v237
	v_cmp_lt_u32_e64 s[50:51], s46, v238
	v_cmp_lt_u32_e64 s[52:53], s47, v237
	v_cmp_lt_u32_e64 s[54:55], s47, v238
	v_readlane_b32 s46, v237, 47
	v_readlane_b32 s47, v238, 47
	v_addc_co_u32_e64 v239, s[56:57], 0, v239, s[48:49]
	v_addc_co_u32_e64 v240, s[56:57], 0, v240, s[50:51]
; DEV void peer_gather_token(const Params& p, int tok) {
;     ...
;   const int e0 = p.eidx[(size_t)tok * 128 + lane], e1 = p.eidx[(size_t)tok * 128 + 64 + lane];
;   const int g0 = __builtin_bit_cast(int, p.gw[(size_t)tok * 128 + lane]), g1 = __builtin_bit_cast(int, p.gw[(size_t)tok * 128 + 64 + lane]);
;   u32x2 dn[4][3], up[4][3];
;   auto issue = [&](int k, int slot) {
;     const int e = (k < 64) ? __builtin_amdgcn_readlane(e0, k) : __builtin_amdgcn_readlane(e1, k - 64);
;     const unsigned char* dr = p.down8 + (size_t)e * ROW6 + lane * 24;
;     const unsigned char* ur = p.up8 + (size_t)e * ROW6 + lane * 24;
; #pragma unroll
;     for (int i = 0; i < 3; ++i) { dn[slot][i] = *(const u32x2*)(dr + i * 8); up[slot][i] = *(const u32x2*)(ur + i * 8); }
;   };
	v_addc_co_u32_e64 v239, s[56:57], 0, v239, s[52:53]
	v_addc_co_u32_e64 v240, s[56:57], 0, v240, s[54:55]
	v_cmp_lt_u32_e64 s[48:49], s46, v237
	v_cmp_lt_u32_e64 s[50:51], s46, v238
	v_cmp_lt_u32_e64 s[52:53], s47, v237
	v_cmp_lt_u32_e64 s[54:55], s47, v238
	v_readlane_b32 s46, v237, 48
	v_readlane_b32 s47, v238, 48
	v_addc_co_u32_e64 v239, s[56:57], 0, v239, s[48:49]
	v_addc_co_u32_e64 v240, s[56:57], 0, v240, s[50:51]
	v_addc_co_u32_e64 v239, s[56:57], 0, v239, s[52:53]
	v_addc_co_u32_e64 v240, s[56:57], 0, v240, s[54:55]
	v_cmp_lt_u32_e64 s[48:49], s46, v237
	v_cmp_lt_u32_e64 s[50:51], s46, v238
	v_cmp_lt_u32_e64 s[52:53], s47, v237
	v_cmp_lt_u32_e64 s[54:55], s47, v238
	v_readlane_b32 s46, v237, 49
	v_readlane_b32 s47, v238, 49
	v_addc_co_u32_e64 v239, s[56:57], 0, v239, s[48:49]
	v_addc_co_u32_e64 v240, s[56:57], 0, v240, s[50:51]
	v_addc_co_u32_e64 v239, s[56:57], 0, v239, s[52:53]
	v_addc_co_u32_e64 v240, s[56:57], 0, v240, s[54:55]
	v_cmp_lt_u32_e64 s[48:49], s46, v237
	v_cmp_lt_u32_e64 s[50:51], s46, v238
	v_cmp_lt_u32_e64 s[52:53], s47, v237
	v_cmp_lt_u32_e64 s[54:55], s47, v238
	v_readlane_b32 s46, v237, 50
	v_readlane_b32 s47, v238, 50
	v_addc_co_u32_e64 v239, s[56:57], 0, v239, s[48:49]
	v_addc_co_u32_e64 v240, s[56:57], 0, v240, s[50:51]
	v_addc_co_u32_e64 v239, s[56:57], 0, v239, s[52:53]
	v_addc_co_u32_e64 v240, s[56:57], 0, v240, s[54:55]
	v_cmp_lt_u32_e64 s[48:49], s46, v237
	v_cmp_lt_u32_e64 s[50:51], s46, v238
	v_cmp_lt_u32_e64 s[52:53], s47, v237
	v_cmp_lt_u32_e64 s[54:55], s47, v238
	v_readlane_b32 s46, v237, 51
	v_readlane_b32 s47, v238, 51
	v_addc_co_u32_e64 v239, s[56:57], 0, v239, s[48:49]
	v_addc_co_u32_e64 v240, s[56:57], 0, v240, s[50:51]
	v_addc_co_u32_e64 v239, s[56:57], 0, v239, s[52:53]
	v_addc_co_u32_e64 v240, s[56:57], 0, v240, s[54:55]
	v_cmp_lt_u32_e64 s[48:49], s46, v237
	v_cmp_lt_u32_e64 s[50:51], s46, v238
	v_cmp_lt_u32_e64 s[52:53], s47, v237
	v_cmp_lt_u32_e64 s[54:55], s47, v238
	v_readlane_b32 s46, v237, 52
	v_readlane_b32 s47, v238, 52
	v_addc_co_u32_e64 v239, s[56:57], 0, v239, s[48:49]
	v_addc_co_u32_e64 v240, s[56:57], 0, v240, s[50:51]
	v_addc_co_u32_e64 v239, s[56:57], 0, v239, s[52:53]
	v_addc_co_u32_e64 v240, s[56:57], 0, v240, s[54:55]
	v_cmp_lt_u32_e64 s[48:49], s46, v237
	v_cmp_lt_u32_e64 s[50:51], s46, v238
	v_cmp_lt_u32_e64 s[52:53], s47, v237
	v_cmp_lt_u32_e64 s[54:55], s47, v238
	v_readlane_b32 s46, v237, 53
	v_readlane_b32 s47, v238, 53
	v_addc_co_u32_e64 v239, s[56:57], 0, v239, s[48:49]
	v_addc_co_u32_e64 v240, s[56:57], 0, v240, s[50:51]
	v_addc_co_u32_e64 v239, s[56:57], 0, v239, s[52:53]
	v_addc_co_u32_e64 v240, s[56:57], 0, v240, s[54:55]
	v_cmp_lt_u32_e64 s[48:49], s46, v237
	v_cmp_lt_u32_e64 s[50:51], s46, v238
	v_cmp_lt_u32_e64 s[52:53], s47, v237
	v_cmp_lt_u32_e64 s[54:55], s47, v238
	v_readlane_b32 s46, v237, 54
	v_readlane_b32 s47, v238, 54
	v_addc_co_u32_e64 v239, s[56:57], 0, v239, s[48:49]
	v_addc_co_u32_e64 v240, s[56:57], 0, v240, s[50:51]
	v_addc_co_u32_e64 v239, s[56:57], 0, v239, s[52:53]
	v_addc_co_u32_e64 v240, s[56:57], 0, v240, s[54:55]
	v_cmp_lt_u32_e64 s[48:49], s46, v237
	v_cmp_lt_u32_e64 s[50:51], s46, v238
	v_cmp_lt_u32_e64 s[52:53], s47, v237
	v_cmp_lt_u32_e64 s[54:55], s47, v238
	v_readlane_b32 s46, v237, 55
	v_readlane_b32 s47, v238, 55
	v_addc_co_u32_e64 v239, s[56:57], 0, v239, s[48:49]
	v_addc_co_u32_e64 v240, s[56:57], 0, v240, s[50:51]
	v_addc_co_u32_e64 v239, s[56:57], 0, v239, s[52:53]
	v_addc_co_u32_e64 v240, s[56:57], 0, v240, s[54:55]
	v_cmp_lt_u32_e64 s[48:49], s46, v237
	v_cmp_lt_u32_e64 s[50:51], s46, v238
	v_cmp_lt_u32_e64 s[52:53], s47, v237
	v_cmp_lt_u32_e64 s[54:55], s47, v238
	v_readlane_b32 s46, v237, 56
	v_readlane_b32 s47, v238, 56
	v_addc_co_u32_e64 v239, s[56:57], 0, v239, s[48:49]
	v_addc_co_u32_e64 v240, s[56:57], 0, v240, s[50:51]
	v_addc_co_u32_e64 v239, s[56:57], 0, v239, s[52:53]
; DEV void peer_gather_token(const Params& p, int tok) {
;     ...
;   const int e0 = p.eidx[(size_t)tok * 128 + lane], e1 = p.eidx[(size_t)tok * 128 + 64 + lane];
;   const int g0 = __builtin_bit_cast(int, p.gw[(size_t)tok * 128 + lane]), g1 = __builtin_bit_cast(int, p.gw[(size_t)tok * 128 + 64 + lane]);
;   u32x2 dn[4][3], up[4][3];
;   auto issue = [&](int k, int slot) {
;     const int e = (k < 64) ? __builtin_amdgcn_readlane(e0, k) : __builtin_amdgcn_readlane(e1, k - 64);
;     const unsigned char* dr = p.down8 + (size_t)e * ROW6 + lane * 24;
;     const unsigned char* ur = p.up8 + (size_t)e * ROW6 + lane * 24;
; #pragma unroll
;     for (int i = 0; i < 3; ++i) { dn[slot][i] = *(const u32x2*)(dr + i * 8); up[slot][i] = *(const u32x2*)(ur + i * 8); }
;   };
	v_addc_co_u32_e64 v240, s[56:57], 0, v240, s[54:55]
	v_cmp_lt_u32_e64 s[48:49], s46, v237
	v_cmp_lt_u32_e64 s[50:51], s46, v238
	v_cmp_lt_u32_e64 s[52:53], s47, v237
	v_cmp_lt_u32_e64 s[54:55], s47, v238
	v_readlane_b32 s46, v237, 57
	v_readlane_b32 s47, v238, 57
	v_addc_co_u32_e64 v239, s[56:57], 0, v239, s[48:49]
	v_addc_co_u32_e64 v240, s[56:57], 0, v240, s[50:51]
	v_addc_co_u32_e64 v239, s[56:57], 0, v239, s[52:53]
	v_addc_co_u32_e64 v240, s[56:57], 0, v240, s[54:55]
	v_cmp_lt_u32_e64 s[48:49], s46, v237
	v_cmp_lt_u32_e64 s[50:51], s46, v238
	v_cmp_lt_u32_e64 s[52:53], s47, v237
	v_cmp_lt_u32_e64 s[54:55], s47, v238
	v_readlane_b32 s46, v237, 58
	v_readlane_b32 s47, v238, 58
	v_addc_co_u32_e64 v239, s[56:57], 0, v239, s[48:49]
	v_addc_co_u32_e64 v240, s[56:57], 0, v240, s[50:51]
	v_addc_co_u32_e64 v239, s[56:57], 0, v239, s[52:53]
	v_addc_co_u32_e64 v240, s[56:57], 0, v240, s[54:55]
	v_cmp_lt_u32_e64 s[48:49], s46, v237
	v_cmp_lt_u32_e64 s[50:51], s46, v238
	v_cmp_lt_u32_e64 s[52:53], s47, v237
	v_cmp_lt_u32_e64 s[54:55], s47, v238
	v_readlane_b32 s46, v237, 59
	v_readlane_b32 s47, v238, 59
	v_addc_co_u32_e64 v239, s[56:57], 0, v239, s[48:49]
	v_addc_co_u32_e64 v240, s[56:57], 0, v240, s[50:51]
	v_addc_co_u32_e64 v239, s[56:57], 0, v239, s[52:53]
	v_addc_co_u32_e64 v240, s[56:57], 0, v240, s[54:55]
	v_cmp_lt_u32_e64 s[48:49], s46, v237
	v_cmp_lt_u32_e64 s[50:51], s46, v238
	v_cmp_lt_u32_e64 s[52:53], s47, v237
	v_cmp_lt_u32_e64 s[54:55], s47, v238
	v_readlane_b32 s46, v237, 60
	v_readlane_b32 s47, v238, 60
	v_addc_co_u32_e64 v239, s[56:57], 0, v239, s[48:49]
	v_addc_co_u32_e64 v240, s[56:57], 0, v240, s[50:51]
	v_addc_co_u32_e64 v239, s[56:57], 0, v239, s[52:53]
	v_addc_co_u32_e64 v240, s[56:57], 0, v240, s[54:55]
	v_cmp_lt_u32_e64 s[48:49], s46, v237
	v_cmp_lt_u32_e64 s[50:51], s46, v238
	v_cmp_lt_u32_e64 s[52:53], s47, v237
	v_cmp_lt_u32_e64 s[54:55], s47, v238
	v_readlane_b32 s46, v237, 61
	v_readlane_b32 s47, v238, 61
	v_addc_co_u32_e64 v239, s[56:57], 0, v239, s[48:49]
	v_addc_co_u32_e64 v240, s[56:57], 0, v240, s[50:51]
	v_addc_co_u32_e64 v239, s[56:57], 0, v239, s[52:53]
	v_addc_co_u32_e64 v240, s[56:57], 0, v240, s[54:55]
	v_cmp_lt_u32_e64 s[48:49], s46, v237
	v_cmp_lt_u32_e64 s[50:51], s46, v238
	v_cmp_lt_u32_e64 s[52:53], s47, v237
	v_cmp_lt_u32_e64 s[54:55], s47, v238
	v_readlane_b32 s46, v237, 62
	v_readlane_b32 s47, v238, 62
	v_addc_co_u32_e64 v239, s[56:57], 0, v239, s[48:49]
	v_addc_co_u32_e64 v240, s[56:57], 0, v240, s[50:51]
	v_addc_co_u32_e64 v239, s[56:57], 0, v239, s[52:53]
	v_addc_co_u32_e64 v240, s[56:57], 0, v240, s[54:55]
	v_cmp_lt_u32_e64 s[48:49], s46, v237
	v_cmp_lt_u32_e64 s[50:51], s46, v238
	v_cmp_lt_u32_e64 s[52:53], s47, v237
	v_cmp_lt_u32_e64 s[54:55], s47, v238
	v_readlane_b32 s46, v237, 63
	v_readlane_b32 s47, v238, 63
	v_addc_co_u32_e64 v239, s[56:57], 0, v239, s[48:49]
	v_addc_co_u32_e64 v240, s[56:57], 0, v240, s[50:51]
	v_addc_co_u32_e64 v239, s[56:57], 0, v239, s[52:53]
	v_addc_co_u32_e64 v240, s[56:57], 0, v240, s[54:55]
	v_cmp_lt_u32_e64 s[48:49], s46, v237
	v_cmp_lt_u32_e64 s[50:51], s46, v238
	v_cmp_lt_u32_e64 s[52:53], s47, v237
	v_cmp_lt_u32_e64 s[54:55], s47, v238
	s_nop 1
	v_addc_co_u32_e64 v239, s[56:57], 0, v239, s[48:49]
	v_addc_co_u32_e64 v240, s[56:57], 0, v240, s[50:51]
	v_addc_co_u32_e64 v239, s[56:57], 0, v239, s[52:53]
	v_addc_co_u32_e64 v240, s[56:57], 0, v240, s[54:55]
	v_xor_b32_e32 v239, s19, v239
	v_xor_b32_e32 v240, s19, v240
	s_xor_b32 s19, s19, 0x7f
	v_and_b32_e32 v237, 0xfffffc00, v241
	v_lshl_add_u32 v239, v239, 2, v237
	v_lshl_add_u32 v240, v240, 2, v237
	ds_write_b32 v239, v216
	ds_write_b32 v240, v217
	ds_write_b32 v239, v218 offset:512
	ds_write_b32 v240, v219 offset:512
	s_waitcnt lgkmcnt(0)
	ds_read_b32 v216, v241
	ds_read_b32 v217, v241 offset:256
	ds_read_b32 v218, v241 offset:512
	ds_read_b32 v219, v241 offset:768
	s_waitcnt lgkmcnt(0)
	s_branch .Lp12_switch
